# LDS-DMA piece setup reordered so the address math fills the M0 wait state (8 s_nop pads removed per loop iteration pair)
# speedup vs baseline: 1.0009x; 1.0009x over previous
.LBB0_523:
	s_cmp_gt_i32 s14, 2
	s_cselect_b32 s9, -3, 2
	s_add_i32 s9, s9, s14
	s_lshl_b32 s12, s9, 13
	s_add_i32 s12, s12, s77
	s_mov_b32 m0, s12
	s_add_u32 s50, s46, 0xffffe000
	s_addc_u32 s51, s47, -1
	global_load_lds_dwordx4 v208, s[50:51]
	s_lshl_b32 s9, s9, 14
	s_add_i32 s9, s9, s61
	s_mov_b32 m0, s9
	s_add_u32 s50, s40, 0xffffc000
	s_addc_u32 s51, s41, -1
	global_load_lds_dwordx4 v208, s[50:51]
	s_addk_i32 s9, 0x2000
	s_mov_b32 m0, s9
	s_add_u32 s50, s40, 0xffffe000
	s_addc_u32 s51, s41, -1
	global_load_lds_dwordx4 v208, s[50:51]
	s_cmp_ge_u32 s67, s55
	s_cselect_b64 s[50:51], -1, 0
	s_and_b64 vcc, exec, s[50:51]
	s_cbranch_vccnz .LBB0_517
.LBB0_524:
	s_cmp_gt_i32 s14, 1
	s_cselect_b32 s9, -2, 3
	s_add_i32 s9, s9, s14
	s_lshl_b32 s12, s9, 13
	s_add_i32 s12, s12, s77
	s_mov_b32 m0, s12
	s_lshl_b32 s9, s9, 14
	global_load_lds_dwordx4 v208, s[46:47]
	s_add_i32 s9, s9, s61
	s_mov_b32 m0, s9
	s_add_u32 s12, s40, 0x2000
	s_addc_u32 s13, s41, 0
	global_load_lds_dwordx4 v208, s[40:41]
	s_addk_i32 s9, 0x2000
	s_mov_b32 m0, s9
	s_nop 0
	global_load_lds_dwordx4 v208, s[12:13]
	s_sub_i32 s9, s66, 64
	s_cmpk_gt_u32 s9, 0x15c
	s_cbranch_scc0 .LBB0_518
	s_branch .LBB0_519

.LBB0_591:
	ds_read_b128 v[2:5], v136
	ds_read_b128 v[6:9], v136 offset:512
	s_waitcnt lgkmcnt(1)
	v_mfma_f32_32x32x16_bf16 v[96:111], v[2:5], v[124:127], 0
	ds_read_b128 v[10:13], v136 offset:2048
	v_cvt_pk_bf16_f32 v128, v64, v65
	v_cvt_pk_bf16_f32 v129, v66, v67
	s_waitcnt lgkmcnt(1)
	v_mfma_f32_32x32x16_bf16 v[80:95], v[6:9], v[124:127], 0
	ds_read_b128 v[2:5], v136 offset:2560
	v_cvt_pk_bf16_f32 v130, v68, v69
	v_cvt_pk_bf16_f32 v131, v70, v71
	s_waitcnt lgkmcnt(1)
	v_mfma_f32_32x32x16_bf16 v[96:111], v[10:13], v[120:123], v[96:111]
	ds_read_b128 v[6:9], v136 offset:4096
	v_mfma_f32_16x16x32_bf16 v[144:147], v[128:131], v[140:143], v[144:147]
	v_cvt_pk_bf16_f32 v10, v72, v73
	v_cvt_pk_bf16_f32 v11, v74, v75
	s_waitcnt lgkmcnt(1)
	v_mfma_f32_32x32x16_bf16 v[80:95], v[2:5], v[120:123], v[80:95]
	ds_read_b128 v[64:67], v136 offset:4608
	v_cvt_pk_bf16_f32 v12, v76, v77
	v_cvt_pk_bf16_f32 v13, v78, v79
	s_waitcnt lgkmcnt(1)
	v_mfma_f32_32x32x16_bf16 v[96:111], v[6:9], v[116:119], v[96:111]
	ds_read_b128 v[2:5], v136 offset:6144
	v_mfma_f32_16x16x32_bf16 v[144:147], v[10:13], v[140:143], v[144:147]
	v_cvt_pk_bf16_f32 v6, v48, v49
	v_cvt_pk_bf16_f32 v7, v50, v51
	s_waitcnt lgkmcnt(1)
	v_mfma_f32_32x32x16_bf16 v[80:95], v[64:67], v[116:119], v[80:95]
	ds_read_b128 v[68:71], v136 offset:6656
	v_cvt_pk_bf16_f32 v8, v52, v53
	v_cvt_pk_bf16_f32 v9, v54, v55
	s_waitcnt lgkmcnt(1)
	v_mfma_f32_32x32x16_bf16 v[96:111], v[2:5], v[112:115], v[96:111]
	v_cvt_pk_bf16_f32 v2, v56, v57
	v_cvt_pk_bf16_f32 v3, v58, v59
	v_mfma_f32_16x16x32_bf16 v[144:147], v[6:9], v[140:143], v[144:147]
	ds_read_b64_tr_b16 v[48:49], v15
	ds_read_b64_tr_b16 v[50:51], v15 offset:1024
	s_waitcnt lgkmcnt(2)
	v_mfma_f32_32x32x16_bf16 v[80:95], v[68:71], v[112:115], v[80:95]
	v_cvt_pk_bf16_f32 v4, v60, v61
	v_cvt_pk_bf16_f32 v5, v62, v63
	ds_read_b64_tr_b16 v[52:53], v15 offset:512
	ds_read_b64_tr_b16 v[54:55], v15 offset:1536
	s_add_i32 s51, s49, -1
	s_cmp_ge_u32 s51, s48
	s_cbranch_scc1 .LBB0_593
	s_cmp_gt_i32 s8, 2
	s_cselect_b32 s54, -3, 2
	s_add_i32 s54, s54, s8
	s_lshl_b32 s55, s54, 13
	s_add_i32 s55, s55, s46
	s_mov_b32 m0, s55
	s_add_u32 s12, s40, 0xffffe000
	s_addc_u32 s13, s41, -1
	global_load_lds_dwordx4 v134, s[12:13]
	s_lshl_b32 s54, s54, 14
	s_add_i32 s54, s54, s47
	s_mov_b32 m0, s54
	s_add_u32 s12, s6, 0xffffe000
	s_addc_u32 s13, s7, -1
	global_load_lds_dwordx4 v134, s[12:13]
.LBB0_593:
	s_cmp_ge_u32 s49, s48
	s_cbranch_scc1 .LBB0_590
	s_cmp_gt_i32 s8, 1
	s_cselect_b32 s12, -2, 3
	s_add_i32 s12, s12, s8
	s_lshl_b32 s13, s12, 13
	s_add_i32 s13, s13, s46
	s_mov_b32 m0, s13
	s_lshl_b32 s12, s12, 14
	global_load_lds_dwordx4 v134, s[40:41]
	s_add_i32 s12, s12, s47
	s_mov_b32 m0, s12
	s_nop 0
	global_load_lds_dwordx4 v134, s[6:7]
	s_branch .LBB0_590
